# v59 + merge-unit epilogues (both instances): g_a*acc+t2 as v_fma_mix_f32 reading the f16 operands directly (per 8 elements 16 cvts + 4 v_pk_fma_f32 -> 8 v_fma_mix_f32)
# speedup vs baseline: 1.0020x; 1.0020x over previous
.LBB0_645:
	v_readlane_b32 s12, v255, 0
	v_or_b32_e32 v130, s54, v143
	v_lshl_or_b32 v131, v142, 11, s55
	s_lshl_b32 s10, s20, 9
	v_readlane_b32 s13, v255, 1
	v_readlane_b32 s14, v255, 2
	v_readlane_b32 s15, v255, 3
	v_readlane_b32 s16, v255, 4
	v_readlane_b32 s17, v255, 5
	v_or_b32_e32 v128, v131, v130
	s_or_b32 s10, s21, s10
	v_readlane_b32 s18, v255, 6
	v_readlane_b32 s19, v255, 7
	s_mov_b64 s[12:13], s[16:17]
	v_add_u32_e32 v128, s10, v128
	s_mov_b64 s[14:15], s[18:19]
	v_mov_b32_e32 v220, v128
	v_add_u32_e32 v221, 0x8000, v128
	v_add_u32_e32 v222, 0x10000, v128
	v_add_u32_e32 v223, 0x18000, v128
	v_add_u32_e32 v224, 0x40000, v128
	v_add_u32_e32 v225, 0x48000, v128
	v_add_u32_e32 v226, 0x50000, v128
	v_add_u32_e32 v227, 0x58000, v128
	global_load_dwordx4 v[156:159], v220, s[24:25]
	global_load_dwordx4 v[160:163], v220, s[14:15]
	global_load_dwordx4 v[164:167], v220, s[24:25] offset:256
	global_load_dwordx4 v[168:171], v220, s[14:15] offset:256
	global_load_dwordx4 v[172:175], v221, s[24:25]
	global_load_dwordx4 v[176:179], v221, s[14:15]
	global_load_dwordx4 v[180:183], v221, s[24:25] offset:256
	global_load_dwordx4 v[184:187], v221, s[14:15] offset:256
	global_load_dwordx4 v[188:191], v222, s[24:25]
	global_load_dwordx4 v[192:195], v222, s[14:15]
	global_load_dwordx4 v[196:199], v222, s[24:25] offset:256
	global_load_dwordx4 v[200:203], v222, s[14:15] offset:256
	global_load_dwordx4 v[204:207], v223, s[24:25]
	global_load_dwordx4 v[208:211], v223, s[14:15]
	global_load_dwordx4 v[212:215], v223, s[24:25] offset:256
	global_load_dwordx4 v[216:219], v223, s[14:15] offset:256
	s_waitcnt vmcnt(14)
	v_fma_mix_f32 v124, v160, v124, v156 op_sel_hi:[1,0,1]
	v_fma_mix_f32 v125, v160, v125, v156 op_sel:[1,0,1] op_sel_hi:[1,0,1]
	v_fma_mix_f32 v126, v161, v126, v157 op_sel_hi:[1,0,1]
	v_fma_mix_f32 v127, v161, v127, v157 op_sel:[1,0,1] op_sel_hi:[1,0,1]
	v_fma_mix_f32 v120, v162, v120, v158 op_sel_hi:[1,0,1]
	v_fma_mix_f32 v121, v162, v121, v158 op_sel:[1,0,1] op_sel_hi:[1,0,1]
	v_fma_mix_f32 v122, v163, v122, v159 op_sel_hi:[1,0,1]
	v_fma_mix_f32 v123, v163, v123, v159 op_sel:[1,0,1] op_sel_hi:[1,0,1]
	v_cvt_pk_f16_f32 v156, v124, v125
	v_cvt_pk_f16_f32 v157, v126, v127
	v_cvt_pk_f16_f32 v158, v120, v121
	v_cvt_pk_f16_f32 v159, v122, v123
	global_store_dwordx4 v220, v[156:159], s[22:23] sc1
	s_nop 1
	global_load_dwordx4 v[156:159], v224, s[24:25]
	global_load_dwordx4 v[160:163], v224, s[14:15]
	s_waitcnt vmcnt(15)
	v_fma_mix_f32 v116, v168, v116, v164 op_sel_hi:[1,0,1]
	v_fma_mix_f32 v117, v168, v117, v164 op_sel:[1,0,1] op_sel_hi:[1,0,1]
	v_fma_mix_f32 v118, v169, v118, v165 op_sel_hi:[1,0,1]
	v_fma_mix_f32 v119, v169, v119, v165 op_sel:[1,0,1] op_sel_hi:[1,0,1]
	v_fma_mix_f32 v112, v170, v112, v166 op_sel_hi:[1,0,1]
	v_fma_mix_f32 v113, v170, v113, v166 op_sel:[1,0,1] op_sel_hi:[1,0,1]
	v_fma_mix_f32 v114, v171, v114, v167 op_sel_hi:[1,0,1]
	v_fma_mix_f32 v115, v171, v115, v167 op_sel:[1,0,1] op_sel_hi:[1,0,1]
	v_cvt_pk_f16_f32 v164, v116, v117
	v_cvt_pk_f16_f32 v165, v118, v119
	v_cvt_pk_f16_f32 v166, v112, v113
	v_cvt_pk_f16_f32 v167, v114, v115
	global_store_dwordx4 v220, v[164:167], s[22:23] offset:256 sc1
	s_nop 1
	global_load_dwordx4 v[164:167], v224, s[24:25] offset:256
	global_load_dwordx4 v[168:171], v224, s[14:15] offset:256
	s_waitcnt vmcnt(16)
	v_fma_mix_f32 v108, v176, v108, v172 op_sel_hi:[1,0,1]
	v_fma_mix_f32 v109, v176, v109, v172 op_sel:[1,0,1] op_sel_hi:[1,0,1]
	v_fma_mix_f32 v110, v177, v110, v173 op_sel_hi:[1,0,1]
	v_fma_mix_f32 v111, v177, v111, v173 op_sel:[1,0,1] op_sel_hi:[1,0,1]
	v_fma_mix_f32 v104, v178, v104, v174 op_sel_hi:[1,0,1]
	v_fma_mix_f32 v105, v178, v105, v174 op_sel:[1,0,1] op_sel_hi:[1,0,1]
	v_fma_mix_f32 v106, v179, v106, v175 op_sel_hi:[1,0,1]
	v_fma_mix_f32 v107, v179, v107, v175 op_sel:[1,0,1] op_sel_hi:[1,0,1]
	v_cvt_pk_f16_f32 v172, v108, v109
	v_cvt_pk_f16_f32 v173, v110, v111
	v_cvt_pk_f16_f32 v174, v104, v105
	v_cvt_pk_f16_f32 v175, v106, v107
	global_store_dwordx4 v221, v[172:175], s[22:23] sc1
	s_nop 1
	global_load_dwordx4 v[172:175], v225, s[24:25]
	global_load_dwordx4 v[176:179], v225, s[14:15]
	s_waitcnt vmcnt(17)
	v_fma_mix_f32 v100, v184, v100, v180 op_sel_hi:[1,0,1]
	v_fma_mix_f32 v101, v184, v101, v180 op_sel:[1,0,1] op_sel_hi:[1,0,1]
	v_fma_mix_f32 v102, v185, v102, v181 op_sel_hi:[1,0,1]
	v_fma_mix_f32 v103, v185, v103, v181 op_sel:[1,0,1] op_sel_hi:[1,0,1]
	v_fma_mix_f32 v96, v186, v96, v182 op_sel_hi:[1,0,1]
	v_fma_mix_f32 v97, v186, v97, v182 op_sel:[1,0,1] op_sel_hi:[1,0,1]
	v_fma_mix_f32 v98, v187, v98, v183 op_sel_hi:[1,0,1]
	v_fma_mix_f32 v99, v187, v99, v183 op_sel:[1,0,1] op_sel_hi:[1,0,1]
	v_cvt_pk_f16_f32 v180, v100, v101
	v_cvt_pk_f16_f32 v181, v102, v103
	v_cvt_pk_f16_f32 v182, v96, v97
	v_cvt_pk_f16_f32 v183, v98, v99
	global_store_dwordx4 v221, v[180:183], s[22:23] offset:256 sc1
	s_nop 1
	global_load_dwordx4 v[180:183], v225, s[24:25] offset:256
	global_load_dwordx4 v[184:187], v225, s[14:15] offset:256
	s_waitcnt vmcnt(18)
	v_fma_mix_f32 v92, v192, v92, v188 op_sel_hi:[1,0,1]
	v_fma_mix_f32 v93, v192, v93, v188 op_sel:[1,0,1] op_sel_hi:[1,0,1]
	v_fma_mix_f32 v94, v193, v94, v189 op_sel_hi:[1,0,1]
	v_fma_mix_f32 v95, v193, v95, v189 op_sel:[1,0,1] op_sel_hi:[1,0,1]
	v_fma_mix_f32 v88, v194, v88, v190 op_sel_hi:[1,0,1]
	v_fma_mix_f32 v89, v194, v89, v190 op_sel:[1,0,1] op_sel_hi:[1,0,1]
	v_fma_mix_f32 v90, v195, v90, v191 op_sel_hi:[1,0,1]
	v_fma_mix_f32 v91, v195, v91, v191 op_sel:[1,0,1] op_sel_hi:[1,0,1]
	v_cvt_pk_f16_f32 v188, v92, v93
	v_cvt_pk_f16_f32 v189, v94, v95
	v_cvt_pk_f16_f32 v190, v88, v89
	v_cvt_pk_f16_f32 v191, v90, v91
	global_store_dwordx4 v222, v[188:191], s[22:23] sc1
	s_nop 1
	global_load_dwordx4 v[188:191], v226, s[24:25]
	global_load_dwordx4 v[192:195], v226, s[14:15]
	s_waitcnt vmcnt(19)
	v_fma_mix_f32 v84, v200, v84, v196 op_sel_hi:[1,0,1]
	v_fma_mix_f32 v85, v200, v85, v196 op_sel:[1,0,1] op_sel_hi:[1,0,1]
	v_fma_mix_f32 v86, v201, v86, v197 op_sel_hi:[1,0,1]
	v_fma_mix_f32 v87, v201, v87, v197 op_sel:[1,0,1] op_sel_hi:[1,0,1]
	v_fma_mix_f32 v80, v202, v80, v198 op_sel_hi:[1,0,1]
	v_fma_mix_f32 v81, v202, v81, v198 op_sel:[1,0,1] op_sel_hi:[1,0,1]
	v_fma_mix_f32 v82, v203, v82, v199 op_sel_hi:[1,0,1]
	v_fma_mix_f32 v83, v203, v83, v199 op_sel:[1,0,1] op_sel_hi:[1,0,1]
	v_cvt_pk_f16_f32 v196, v84, v85
	v_cvt_pk_f16_f32 v197, v86, v87
	v_cvt_pk_f16_f32 v198, v80, v81
	v_cvt_pk_f16_f32 v199, v82, v83
	global_store_dwordx4 v222, v[196:199], s[22:23] offset:256 sc1
	s_nop 1
	global_load_dwordx4 v[196:199], v226, s[24:25] offset:256
	global_load_dwordx4 v[200:203], v226, s[14:15] offset:256
	s_waitcnt vmcnt(20)
	v_fma_mix_f32 v76, v208, v76, v204 op_sel_hi:[1,0,1]
	v_fma_mix_f32 v77, v208, v77, v204 op_sel:[1,0,1] op_sel_hi:[1,0,1]
	v_fma_mix_f32 v78, v209, v78, v205 op_sel_hi:[1,0,1]
	v_fma_mix_f32 v79, v209, v79, v205 op_sel:[1,0,1] op_sel_hi:[1,0,1]
	v_fma_mix_f32 v72, v210, v72, v206 op_sel_hi:[1,0,1]
	v_fma_mix_f32 v73, v210, v73, v206 op_sel:[1,0,1] op_sel_hi:[1,0,1]
	v_fma_mix_f32 v74, v211, v74, v207 op_sel_hi:[1,0,1]
	v_fma_mix_f32 v75, v211, v75, v207 op_sel:[1,0,1] op_sel_hi:[1,0,1]
	v_cvt_pk_f16_f32 v204, v76, v77
	v_cvt_pk_f16_f32 v205, v78, v79
	v_cvt_pk_f16_f32 v206, v72, v73
	v_cvt_pk_f16_f32 v207, v74, v75
	global_store_dwordx4 v223, v[204:207], s[22:23] sc1
	s_nop 1
	global_load_dwordx4 v[204:207], v227, s[24:25]
	global_load_dwordx4 v[208:211], v227, s[14:15]
	s_waitcnt vmcnt(21)
	v_fma_mix_f32 v68, v216, v68, v212 op_sel_hi:[1,0,1]
	v_fma_mix_f32 v69, v216, v69, v212 op_sel:[1,0,1] op_sel_hi:[1,0,1]
	v_fma_mix_f32 v70, v217, v70, v213 op_sel_hi:[1,0,1]
	v_fma_mix_f32 v71, v217, v71, v213 op_sel:[1,0,1] op_sel_hi:[1,0,1]
	v_fma_mix_f32 v64, v218, v64, v214 op_sel_hi:[1,0,1]
	v_fma_mix_f32 v65, v218, v65, v214 op_sel:[1,0,1] op_sel_hi:[1,0,1]
	v_fma_mix_f32 v66, v219, v66, v215 op_sel_hi:[1,0,1]
	v_fma_mix_f32 v67, v219, v67, v215 op_sel:[1,0,1] op_sel_hi:[1,0,1]
	v_cvt_pk_f16_f32 v212, v68, v69
	v_cvt_pk_f16_f32 v213, v70, v71
	v_cvt_pk_f16_f32 v214, v64, v65
	v_cvt_pk_f16_f32 v215, v66, v67
	global_store_dwordx4 v223, v[212:215], s[22:23] offset:256 sc1
	s_nop 1
	global_load_dwordx4 v[212:215], v227, s[24:25] offset:256
	global_load_dwordx4 v[216:219], v227, s[14:15] offset:256
	s_waitcnt vmcnt(21)
	v_fma_mix_f32 v60, v160, v60, v156 op_sel_hi:[1,0,1]
	v_fma_mix_f32 v61, v160, v61, v156 op_sel:[1,0,1] op_sel_hi:[1,0,1]
	v_fma_mix_f32 v62, v161, v62, v157 op_sel_hi:[1,0,1]
	v_fma_mix_f32 v63, v161, v63, v157 op_sel:[1,0,1] op_sel_hi:[1,0,1]
	v_fma_mix_f32 v56, v162, v56, v158 op_sel_hi:[1,0,1]
	v_fma_mix_f32 v57, v162, v57, v158 op_sel:[1,0,1] op_sel_hi:[1,0,1]
	v_fma_mix_f32 v58, v163, v58, v159 op_sel_hi:[1,0,1]
	v_fma_mix_f32 v59, v163, v59, v159 op_sel:[1,0,1] op_sel_hi:[1,0,1]
	v_cvt_pk_f16_f32 v156, v60, v61
	v_cvt_pk_f16_f32 v157, v62, v63
	v_cvt_pk_f16_f32 v158, v56, v57
	v_cvt_pk_f16_f32 v159, v58, v59
	global_store_dwordx4 v224, v[156:159], s[22:23] sc1
	s_waitcnt vmcnt(19)
	v_fma_mix_f32 v52, v168, v52, v164 op_sel_hi:[1,0,1]
	v_fma_mix_f32 v53, v168, v53, v164 op_sel:[1,0,1] op_sel_hi:[1,0,1]
	v_fma_mix_f32 v54, v169, v54, v165 op_sel_hi:[1,0,1]
	v_fma_mix_f32 v55, v169, v55, v165 op_sel:[1,0,1] op_sel_hi:[1,0,1]
	v_fma_mix_f32 v48, v170, v48, v166 op_sel_hi:[1,0,1]
	v_fma_mix_f32 v49, v170, v49, v166 op_sel:[1,0,1] op_sel_hi:[1,0,1]
	v_fma_mix_f32 v50, v171, v50, v167 op_sel_hi:[1,0,1]
	v_fma_mix_f32 v51, v171, v51, v167 op_sel:[1,0,1] op_sel_hi:[1,0,1]
	v_cvt_pk_f16_f32 v164, v52, v53
	v_cvt_pk_f16_f32 v165, v54, v55
	v_cvt_pk_f16_f32 v166, v48, v49
	v_cvt_pk_f16_f32 v167, v50, v51
	global_store_dwordx4 v224, v[164:167], s[22:23] offset:256 sc1
	s_waitcnt vmcnt(17)
	v_fma_mix_f32 v44, v176, v44, v172 op_sel_hi:[1,0,1]
	v_fma_mix_f32 v45, v176, v45, v172 op_sel:[1,0,1] op_sel_hi:[1,0,1]
	v_fma_mix_f32 v46, v177, v46, v173 op_sel_hi:[1,0,1]
	v_fma_mix_f32 v47, v177, v47, v173 op_sel:[1,0,1] op_sel_hi:[1,0,1]
	v_fma_mix_f32 v40, v178, v40, v174 op_sel_hi:[1,0,1]
	v_fma_mix_f32 v41, v178, v41, v174 op_sel:[1,0,1] op_sel_hi:[1,0,1]
	v_fma_mix_f32 v42, v179, v42, v175 op_sel_hi:[1,0,1]
	v_fma_mix_f32 v43, v179, v43, v175 op_sel:[1,0,1] op_sel_hi:[1,0,1]
	v_cvt_pk_f16_f32 v172, v44, v45
	v_cvt_pk_f16_f32 v173, v46, v47
	v_cvt_pk_f16_f32 v174, v40, v41
	v_cvt_pk_f16_f32 v175, v42, v43
	global_store_dwordx4 v225, v[172:175], s[22:23] sc1
	s_waitcnt vmcnt(15)
	v_fma_mix_f32 v36, v184, v36, v180 op_sel_hi:[1,0,1]
	v_fma_mix_f32 v37, v184, v37, v180 op_sel:[1,0,1] op_sel_hi:[1,0,1]
	v_fma_mix_f32 v38, v185, v38, v181 op_sel_hi:[1,0,1]
	v_fma_mix_f32 v39, v185, v39, v181 op_sel:[1,0,1] op_sel_hi:[1,0,1]
	v_fma_mix_f32 v32, v186, v32, v182 op_sel_hi:[1,0,1]
	v_fma_mix_f32 v33, v186, v33, v182 op_sel:[1,0,1] op_sel_hi:[1,0,1]
	v_fma_mix_f32 v34, v187, v34, v183 op_sel_hi:[1,0,1]
	v_fma_mix_f32 v35, v187, v35, v183 op_sel:[1,0,1] op_sel_hi:[1,0,1]
	v_cvt_pk_f16_f32 v180, v36, v37
	v_cvt_pk_f16_f32 v181, v38, v39
	v_cvt_pk_f16_f32 v182, v32, v33
	v_cvt_pk_f16_f32 v183, v34, v35
	global_store_dwordx4 v225, v[180:183], s[22:23] offset:256 sc1
	s_waitcnt vmcnt(13)
	v_fma_mix_f32 v28, v192, v28, v188 op_sel_hi:[1,0,1]
	v_fma_mix_f32 v29, v192, v29, v188 op_sel:[1,0,1] op_sel_hi:[1,0,1]
	v_fma_mix_f32 v30, v193, v30, v189 op_sel_hi:[1,0,1]
	v_fma_mix_f32 v31, v193, v31, v189 op_sel:[1,0,1] op_sel_hi:[1,0,1]
	v_fma_mix_f32 v24, v194, v24, v190 op_sel_hi:[1,0,1]
	v_fma_mix_f32 v25, v194, v25, v190 op_sel:[1,0,1] op_sel_hi:[1,0,1]
	v_fma_mix_f32 v26, v195, v26, v191 op_sel_hi:[1,0,1]
	v_fma_mix_f32 v27, v195, v27, v191 op_sel:[1,0,1] op_sel_hi:[1,0,1]
	v_cvt_pk_f16_f32 v188, v28, v29
	v_cvt_pk_f16_f32 v189, v30, v31
	v_cvt_pk_f16_f32 v190, v24, v25
	v_cvt_pk_f16_f32 v191, v26, v27
	global_store_dwordx4 v226, v[188:191], s[22:23] sc1
	s_waitcnt vmcnt(11)
	v_fma_mix_f32 v20, v200, v20, v196 op_sel_hi:[1,0,1]
	v_fma_mix_f32 v21, v200, v21, v196 op_sel:[1,0,1] op_sel_hi:[1,0,1]
	v_fma_mix_f32 v22, v201, v22, v197 op_sel_hi:[1,0,1]
	v_fma_mix_f32 v23, v201, v23, v197 op_sel:[1,0,1] op_sel_hi:[1,0,1]
	v_fma_mix_f32 v16, v202, v16, v198 op_sel_hi:[1,0,1]
	v_fma_mix_f32 v17, v202, v17, v198 op_sel:[1,0,1] op_sel_hi:[1,0,1]
	v_fma_mix_f32 v18, v203, v18, v199 op_sel_hi:[1,0,1]
	v_fma_mix_f32 v19, v203, v19, v199 op_sel:[1,0,1] op_sel_hi:[1,0,1]
	v_cvt_pk_f16_f32 v196, v20, v21
	v_cvt_pk_f16_f32 v197, v22, v23
	v_cvt_pk_f16_f32 v198, v16, v17
	v_cvt_pk_f16_f32 v199, v18, v19
	global_store_dwordx4 v226, v[196:199], s[22:23] offset:256 sc1
	s_waitcnt vmcnt(9)
	v_fma_mix_f32 v12, v208, v12, v204 op_sel_hi:[1,0,1]
	v_fma_mix_f32 v13, v208, v13, v204 op_sel:[1,0,1] op_sel_hi:[1,0,1]
	v_fma_mix_f32 v14, v209, v14, v205 op_sel_hi:[1,0,1]
	v_fma_mix_f32 v15, v209, v15, v205 op_sel:[1,0,1] op_sel_hi:[1,0,1]
	v_fma_mix_f32 v8, v210, v8, v206 op_sel_hi:[1,0,1]
	v_fma_mix_f32 v9, v210, v9, v206 op_sel:[1,0,1] op_sel_hi:[1,0,1]
	v_fma_mix_f32 v10, v211, v10, v207 op_sel_hi:[1,0,1]
	v_fma_mix_f32 v11, v211, v11, v207 op_sel:[1,0,1] op_sel_hi:[1,0,1]
	v_cvt_pk_f16_f32 v204, v12, v13
	v_cvt_pk_f16_f32 v205, v14, v15
	v_cvt_pk_f16_f32 v206, v8, v9
	v_cvt_pk_f16_f32 v207, v10, v11
	global_store_dwordx4 v227, v[204:207], s[22:23] sc1
	s_waitcnt vmcnt(7)
	v_fma_mix_f32 v4, v216, v4, v212 op_sel_hi:[1,0,1]
	v_fma_mix_f32 v5, v216, v5, v212 op_sel:[1,0,1] op_sel_hi:[1,0,1]
	v_fma_mix_f32 v6, v217, v6, v213 op_sel_hi:[1,0,1]
	v_fma_mix_f32 v7, v217, v7, v213 op_sel:[1,0,1] op_sel_hi:[1,0,1]
	v_fma_mix_f32 v0, v218, v0, v214 op_sel_hi:[1,0,1]
	v_fma_mix_f32 v1, v218, v1, v214 op_sel:[1,0,1] op_sel_hi:[1,0,1]
	v_fma_mix_f32 v2, v219, v2, v215 op_sel_hi:[1,0,1]
	v_fma_mix_f32 v3, v219, v3, v215 op_sel:[1,0,1] op_sel_hi:[1,0,1]
	v_cvt_pk_f16_f32 v212, v4, v5
	v_cvt_pk_f16_f32 v213, v6, v7
	v_cvt_pk_f16_f32 v214, v0, v1
	v_cvt_pk_f16_f32 v215, v2, v3
	global_store_dwordx4 v227, v[212:215], s[22:23] offset:256 sc1
	s_waitcnt vmcnt(0)
	s_barrier
	v_mbcnt_lo_u32_b32 v0, -1, 0
	v_mbcnt_hi_u32_b32 v0, -1, v0
	s_nop 0
	v_or_b32_e32 v0, s97, v0
	v_cmp_eq_u32_e32 vcc, 0, v0
	s_and_saveexec_b64 s[10:11], vcc
	s_cbranch_execz .LBB0_596
	s_mov_b64 s[14:15], exec
	v_mbcnt_lo_u32_b32 v0, s14, 0
	v_mbcnt_hi_u32_b32 v0, s15, v0
	v_cmp_eq_u32_e32 vcc, 0, v0
	s_and_saveexec_b64 s[12:13], vcc
	s_cbranch_execz .LBB0_648
	s_lshl_b32 s0, s0, 6
	s_lshl_b64 s[16:17], s[0:1], 2
	s_add_u32 s16, s56, s16
	s_addc_u32 s17, s57, s17
	s_bcnt1_i32_b64 s0, s[14:15]
	v_mov_b32_e32 v0, s0
	global_atomic_add v129, v0, s[16:17]

.LBB0_1235:
	v_readlane_b32 s12, v255, 0
	v_or_b32_e32 v130, s54, v143
	v_lshl_or_b32 v131, v142, 11, s55
	s_lshl_b32 s10, s20, 9
	v_readlane_b32 s13, v255, 1
	v_readlane_b32 s14, v255, 2
	v_readlane_b32 s15, v255, 3
	v_readlane_b32 s16, v255, 4
	v_readlane_b32 s17, v255, 5
	v_or_b32_e32 v128, v131, v130
	s_or_b32 s10, s21, s10
	v_readlane_b32 s18, v255, 6
	v_readlane_b32 s19, v255, 7
	s_mov_b64 s[12:13], s[16:17]
	v_add_u32_e32 v128, s10, v128
	s_mov_b64 s[14:15], s[18:19]
	v_mov_b32_e32 v220, v128
	v_add_u32_e32 v221, 0x8000, v128
	v_add_u32_e32 v222, 0x10000, v128
	v_add_u32_e32 v223, 0x18000, v128
	v_add_u32_e32 v224, 0x40000, v128
	v_add_u32_e32 v225, 0x48000, v128
	v_add_u32_e32 v226, 0x50000, v128
	v_add_u32_e32 v227, 0x58000, v128
	global_load_dwordx4 v[156:159], v220, s[24:25]
	global_load_dwordx4 v[160:163], v220, s[14:15]
	global_load_dwordx4 v[164:167], v220, s[24:25] offset:256
	global_load_dwordx4 v[168:171], v220, s[14:15] offset:256
	global_load_dwordx4 v[172:175], v221, s[24:25]
	global_load_dwordx4 v[176:179], v221, s[14:15]
	global_load_dwordx4 v[180:183], v221, s[24:25] offset:256
	global_load_dwordx4 v[184:187], v221, s[14:15] offset:256
	global_load_dwordx4 v[188:191], v222, s[24:25]
	global_load_dwordx4 v[192:195], v222, s[14:15]
	global_load_dwordx4 v[196:199], v222, s[24:25] offset:256
	global_load_dwordx4 v[200:203], v222, s[14:15] offset:256
	global_load_dwordx4 v[204:207], v223, s[24:25]
	global_load_dwordx4 v[208:211], v223, s[14:15]
	global_load_dwordx4 v[212:215], v223, s[24:25] offset:256
	global_load_dwordx4 v[216:219], v223, s[14:15] offset:256
	s_waitcnt vmcnt(14)
	v_fma_mix_f32 v124, v160, v124, v156 op_sel_hi:[1,0,1]
	v_fma_mix_f32 v125, v160, v125, v156 op_sel:[1,0,1] op_sel_hi:[1,0,1]
	v_fma_mix_f32 v126, v161, v126, v157 op_sel_hi:[1,0,1]
	v_fma_mix_f32 v127, v161, v127, v157 op_sel:[1,0,1] op_sel_hi:[1,0,1]
	v_fma_mix_f32 v120, v162, v120, v158 op_sel_hi:[1,0,1]
	v_fma_mix_f32 v121, v162, v121, v158 op_sel:[1,0,1] op_sel_hi:[1,0,1]
	v_fma_mix_f32 v122, v163, v122, v159 op_sel_hi:[1,0,1]
	v_fma_mix_f32 v123, v163, v123, v159 op_sel:[1,0,1] op_sel_hi:[1,0,1]
	v_cvt_pk_f16_f32 v156, v124, v125
	v_cvt_pk_f16_f32 v157, v126, v127
	v_cvt_pk_f16_f32 v158, v120, v121
	v_cvt_pk_f16_f32 v159, v122, v123
	global_store_dwordx4 v220, v[156:159], s[22:23] sc1
	s_nop 1
	global_load_dwordx4 v[156:159], v224, s[24:25]
	global_load_dwordx4 v[160:163], v224, s[14:15]
	s_waitcnt vmcnt(15)
	v_fma_mix_f32 v116, v168, v116, v164 op_sel_hi:[1,0,1]
	v_fma_mix_f32 v117, v168, v117, v164 op_sel:[1,0,1] op_sel_hi:[1,0,1]
	v_fma_mix_f32 v118, v169, v118, v165 op_sel_hi:[1,0,1]
	v_fma_mix_f32 v119, v169, v119, v165 op_sel:[1,0,1] op_sel_hi:[1,0,1]
	v_fma_mix_f32 v112, v170, v112, v166 op_sel_hi:[1,0,1]
	v_fma_mix_f32 v113, v170, v113, v166 op_sel:[1,0,1] op_sel_hi:[1,0,1]
	v_fma_mix_f32 v114, v171, v114, v167 op_sel_hi:[1,0,1]
	v_fma_mix_f32 v115, v171, v115, v167 op_sel:[1,0,1] op_sel_hi:[1,0,1]
	v_cvt_pk_f16_f32 v164, v116, v117
	v_cvt_pk_f16_f32 v165, v118, v119
	v_cvt_pk_f16_f32 v166, v112, v113
	v_cvt_pk_f16_f32 v167, v114, v115
	global_store_dwordx4 v220, v[164:167], s[22:23] offset:256 sc1
	s_nop 1
	global_load_dwordx4 v[164:167], v224, s[24:25] offset:256
	global_load_dwordx4 v[168:171], v224, s[14:15] offset:256
	s_waitcnt vmcnt(16)
	v_fma_mix_f32 v108, v176, v108, v172 op_sel_hi:[1,0,1]
	v_fma_mix_f32 v109, v176, v109, v172 op_sel:[1,0,1] op_sel_hi:[1,0,1]
	v_fma_mix_f32 v110, v177, v110, v173 op_sel_hi:[1,0,1]
	v_fma_mix_f32 v111, v177, v111, v173 op_sel:[1,0,1] op_sel_hi:[1,0,1]
	v_fma_mix_f32 v104, v178, v104, v174 op_sel_hi:[1,0,1]
	v_fma_mix_f32 v105, v178, v105, v174 op_sel:[1,0,1] op_sel_hi:[1,0,1]
	v_fma_mix_f32 v106, v179, v106, v175 op_sel_hi:[1,0,1]
	v_fma_mix_f32 v107, v179, v107, v175 op_sel:[1,0,1] op_sel_hi:[1,0,1]
	v_cvt_pk_f16_f32 v172, v108, v109
	v_cvt_pk_f16_f32 v173, v110, v111
	v_cvt_pk_f16_f32 v174, v104, v105
	v_cvt_pk_f16_f32 v175, v106, v107
	global_store_dwordx4 v221, v[172:175], s[22:23] sc1
	s_nop 1
	global_load_dwordx4 v[172:175], v225, s[24:25]
	global_load_dwordx4 v[176:179], v225, s[14:15]
	s_waitcnt vmcnt(17)
	v_fma_mix_f32 v100, v184, v100, v180 op_sel_hi:[1,0,1]
	v_fma_mix_f32 v101, v184, v101, v180 op_sel:[1,0,1] op_sel_hi:[1,0,1]
	v_fma_mix_f32 v102, v185, v102, v181 op_sel_hi:[1,0,1]
	v_fma_mix_f32 v103, v185, v103, v181 op_sel:[1,0,1] op_sel_hi:[1,0,1]
	v_fma_mix_f32 v96, v186, v96, v182 op_sel_hi:[1,0,1]
	v_fma_mix_f32 v97, v186, v97, v182 op_sel:[1,0,1] op_sel_hi:[1,0,1]
	v_fma_mix_f32 v98, v187, v98, v183 op_sel_hi:[1,0,1]
	v_fma_mix_f32 v99, v187, v99, v183 op_sel:[1,0,1] op_sel_hi:[1,0,1]
	v_cvt_pk_f16_f32 v180, v100, v101
	v_cvt_pk_f16_f32 v181, v102, v103
	v_cvt_pk_f16_f32 v182, v96, v97
	v_cvt_pk_f16_f32 v183, v98, v99
	global_store_dwordx4 v221, v[180:183], s[22:23] offset:256 sc1
	s_nop 1
	global_load_dwordx4 v[180:183], v225, s[24:25] offset:256
	global_load_dwordx4 v[184:187], v225, s[14:15] offset:256
	s_waitcnt vmcnt(18)
	v_fma_mix_f32 v92, v192, v92, v188 op_sel_hi:[1,0,1]
	v_fma_mix_f32 v93, v192, v93, v188 op_sel:[1,0,1] op_sel_hi:[1,0,1]
	v_fma_mix_f32 v94, v193, v94, v189 op_sel_hi:[1,0,1]
	v_fma_mix_f32 v95, v193, v95, v189 op_sel:[1,0,1] op_sel_hi:[1,0,1]
	v_fma_mix_f32 v88, v194, v88, v190 op_sel_hi:[1,0,1]
	v_fma_mix_f32 v89, v194, v89, v190 op_sel:[1,0,1] op_sel_hi:[1,0,1]
	v_fma_mix_f32 v90, v195, v90, v191 op_sel_hi:[1,0,1]
	v_fma_mix_f32 v91, v195, v91, v191 op_sel:[1,0,1] op_sel_hi:[1,0,1]
	v_cvt_pk_f16_f32 v188, v92, v93
	v_cvt_pk_f16_f32 v189, v94, v95
	v_cvt_pk_f16_f32 v190, v88, v89
	v_cvt_pk_f16_f32 v191, v90, v91
	global_store_dwordx4 v222, v[188:191], s[22:23] sc1
	s_nop 1
	global_load_dwordx4 v[188:191], v226, s[24:25]
	global_load_dwordx4 v[192:195], v226, s[14:15]
	s_waitcnt vmcnt(19)
	v_fma_mix_f32 v84, v200, v84, v196 op_sel_hi:[1,0,1]
	v_fma_mix_f32 v85, v200, v85, v196 op_sel:[1,0,1] op_sel_hi:[1,0,1]
	v_fma_mix_f32 v86, v201, v86, v197 op_sel_hi:[1,0,1]
	v_fma_mix_f32 v87, v201, v87, v197 op_sel:[1,0,1] op_sel_hi:[1,0,1]
	v_fma_mix_f32 v80, v202, v80, v198 op_sel_hi:[1,0,1]
	v_fma_mix_f32 v81, v202, v81, v198 op_sel:[1,0,1] op_sel_hi:[1,0,1]
	v_fma_mix_f32 v82, v203, v82, v199 op_sel_hi:[1,0,1]
	v_fma_mix_f32 v83, v203, v83, v199 op_sel:[1,0,1] op_sel_hi:[1,0,1]
	v_cvt_pk_f16_f32 v196, v84, v85
	v_cvt_pk_f16_f32 v197, v86, v87
	v_cvt_pk_f16_f32 v198, v80, v81
	v_cvt_pk_f16_f32 v199, v82, v83
	global_store_dwordx4 v222, v[196:199], s[22:23] offset:256 sc1
	s_nop 1
	global_load_dwordx4 v[196:199], v226, s[24:25] offset:256
	global_load_dwordx4 v[200:203], v226, s[14:15] offset:256
	s_waitcnt vmcnt(20)
	v_fma_mix_f32 v76, v208, v76, v204 op_sel_hi:[1,0,1]
	v_fma_mix_f32 v77, v208, v77, v204 op_sel:[1,0,1] op_sel_hi:[1,0,1]
	v_fma_mix_f32 v78, v209, v78, v205 op_sel_hi:[1,0,1]
	v_fma_mix_f32 v79, v209, v79, v205 op_sel:[1,0,1] op_sel_hi:[1,0,1]
	v_fma_mix_f32 v72, v210, v72, v206 op_sel_hi:[1,0,1]
	v_fma_mix_f32 v73, v210, v73, v206 op_sel:[1,0,1] op_sel_hi:[1,0,1]
	v_fma_mix_f32 v74, v211, v74, v207 op_sel_hi:[1,0,1]
	v_fma_mix_f32 v75, v211, v75, v207 op_sel:[1,0,1] op_sel_hi:[1,0,1]
	v_cvt_pk_f16_f32 v204, v76, v77
	v_cvt_pk_f16_f32 v205, v78, v79
	v_cvt_pk_f16_f32 v206, v72, v73
	v_cvt_pk_f16_f32 v207, v74, v75
	global_store_dwordx4 v223, v[204:207], s[22:23] sc1
	s_nop 1
	global_load_dwordx4 v[204:207], v227, s[24:25]
	global_load_dwordx4 v[208:211], v227, s[14:15]
	s_waitcnt vmcnt(21)
	v_fma_mix_f32 v68, v216, v68, v212 op_sel_hi:[1,0,1]
	v_fma_mix_f32 v69, v216, v69, v212 op_sel:[1,0,1] op_sel_hi:[1,0,1]
	v_fma_mix_f32 v70, v217, v70, v213 op_sel_hi:[1,0,1]
	v_fma_mix_f32 v71, v217, v71, v213 op_sel:[1,0,1] op_sel_hi:[1,0,1]
	v_fma_mix_f32 v64, v218, v64, v214 op_sel_hi:[1,0,1]
	v_fma_mix_f32 v65, v218, v65, v214 op_sel:[1,0,1] op_sel_hi:[1,0,1]
	v_fma_mix_f32 v66, v219, v66, v215 op_sel_hi:[1,0,1]
	v_fma_mix_f32 v67, v219, v67, v215 op_sel:[1,0,1] op_sel_hi:[1,0,1]
	v_cvt_pk_f16_f32 v212, v68, v69
	v_cvt_pk_f16_f32 v213, v70, v71
	v_cvt_pk_f16_f32 v214, v64, v65
	v_cvt_pk_f16_f32 v215, v66, v67
	global_store_dwordx4 v223, v[212:215], s[22:23] offset:256 sc1
	s_nop 1
	global_load_dwordx4 v[212:215], v227, s[24:25] offset:256
	global_load_dwordx4 v[216:219], v227, s[14:15] offset:256
	s_waitcnt vmcnt(21)
	v_fma_mix_f32 v60, v160, v60, v156 op_sel_hi:[1,0,1]
	v_fma_mix_f32 v61, v160, v61, v156 op_sel:[1,0,1] op_sel_hi:[1,0,1]
	v_fma_mix_f32 v62, v161, v62, v157 op_sel_hi:[1,0,1]
	v_fma_mix_f32 v63, v161, v63, v157 op_sel:[1,0,1] op_sel_hi:[1,0,1]
	v_fma_mix_f32 v56, v162, v56, v158 op_sel_hi:[1,0,1]
	v_fma_mix_f32 v57, v162, v57, v158 op_sel:[1,0,1] op_sel_hi:[1,0,1]
	v_fma_mix_f32 v58, v163, v58, v159 op_sel_hi:[1,0,1]
	v_fma_mix_f32 v59, v163, v59, v159 op_sel:[1,0,1] op_sel_hi:[1,0,1]
	v_cvt_pk_f16_f32 v156, v60, v61
	v_cvt_pk_f16_f32 v157, v62, v63
	v_cvt_pk_f16_f32 v158, v56, v57
	v_cvt_pk_f16_f32 v159, v58, v59
	global_store_dwordx4 v224, v[156:159], s[22:23] sc1
	s_waitcnt vmcnt(19)
	v_fma_mix_f32 v52, v168, v52, v164 op_sel_hi:[1,0,1]
	v_fma_mix_f32 v53, v168, v53, v164 op_sel:[1,0,1] op_sel_hi:[1,0,1]
	v_fma_mix_f32 v54, v169, v54, v165 op_sel_hi:[1,0,1]
	v_fma_mix_f32 v55, v169, v55, v165 op_sel:[1,0,1] op_sel_hi:[1,0,1]
	v_fma_mix_f32 v48, v170, v48, v166 op_sel_hi:[1,0,1]
	v_fma_mix_f32 v49, v170, v49, v166 op_sel:[1,0,1] op_sel_hi:[1,0,1]
	v_fma_mix_f32 v50, v171, v50, v167 op_sel_hi:[1,0,1]
	v_fma_mix_f32 v51, v171, v51, v167 op_sel:[1,0,1] op_sel_hi:[1,0,1]
	v_cvt_pk_f16_f32 v164, v52, v53
	v_cvt_pk_f16_f32 v165, v54, v55
	v_cvt_pk_f16_f32 v166, v48, v49
	v_cvt_pk_f16_f32 v167, v50, v51
	global_store_dwordx4 v224, v[164:167], s[22:23] offset:256 sc1
	s_waitcnt vmcnt(17)
	v_fma_mix_f32 v44, v176, v44, v172 op_sel_hi:[1,0,1]
	v_fma_mix_f32 v45, v176, v45, v172 op_sel:[1,0,1] op_sel_hi:[1,0,1]
	v_fma_mix_f32 v46, v177, v46, v173 op_sel_hi:[1,0,1]
	v_fma_mix_f32 v47, v177, v47, v173 op_sel:[1,0,1] op_sel_hi:[1,0,1]
	v_fma_mix_f32 v40, v178, v40, v174 op_sel_hi:[1,0,1]
	v_fma_mix_f32 v41, v178, v41, v174 op_sel:[1,0,1] op_sel_hi:[1,0,1]
	v_fma_mix_f32 v42, v179, v42, v175 op_sel_hi:[1,0,1]
	v_fma_mix_f32 v43, v179, v43, v175 op_sel:[1,0,1] op_sel_hi:[1,0,1]
	v_cvt_pk_f16_f32 v172, v44, v45
	v_cvt_pk_f16_f32 v173, v46, v47
	v_cvt_pk_f16_f32 v174, v40, v41
	v_cvt_pk_f16_f32 v175, v42, v43
	global_store_dwordx4 v225, v[172:175], s[22:23] sc1
	s_waitcnt vmcnt(15)
	v_fma_mix_f32 v36, v184, v36, v180 op_sel_hi:[1,0,1]
	v_fma_mix_f32 v37, v184, v37, v180 op_sel:[1,0,1] op_sel_hi:[1,0,1]
	v_fma_mix_f32 v38, v185, v38, v181 op_sel_hi:[1,0,1]
	v_fma_mix_f32 v39, v185, v39, v181 op_sel:[1,0,1] op_sel_hi:[1,0,1]
	v_fma_mix_f32 v32, v186, v32, v182 op_sel_hi:[1,0,1]
	v_fma_mix_f32 v33, v186, v33, v182 op_sel:[1,0,1] op_sel_hi:[1,0,1]
	v_fma_mix_f32 v34, v187, v34, v183 op_sel_hi:[1,0,1]
	v_fma_mix_f32 v35, v187, v35, v183 op_sel:[1,0,1] op_sel_hi:[1,0,1]
	v_cvt_pk_f16_f32 v180, v36, v37
	v_cvt_pk_f16_f32 v181, v38, v39
	v_cvt_pk_f16_f32 v182, v32, v33
	v_cvt_pk_f16_f32 v183, v34, v35
	global_store_dwordx4 v225, v[180:183], s[22:23] offset:256 sc1
	s_waitcnt vmcnt(13)
	v_fma_mix_f32 v28, v192, v28, v188 op_sel_hi:[1,0,1]
	v_fma_mix_f32 v29, v192, v29, v188 op_sel:[1,0,1] op_sel_hi:[1,0,1]
	v_fma_mix_f32 v30, v193, v30, v189 op_sel_hi:[1,0,1]
	v_fma_mix_f32 v31, v193, v31, v189 op_sel:[1,0,1] op_sel_hi:[1,0,1]
	v_fma_mix_f32 v24, v194, v24, v190 op_sel_hi:[1,0,1]
	v_fma_mix_f32 v25, v194, v25, v190 op_sel:[1,0,1] op_sel_hi:[1,0,1]
	v_fma_mix_f32 v26, v195, v26, v191 op_sel_hi:[1,0,1]
	v_fma_mix_f32 v27, v195, v27, v191 op_sel:[1,0,1] op_sel_hi:[1,0,1]
	v_cvt_pk_f16_f32 v188, v28, v29
	v_cvt_pk_f16_f32 v189, v30, v31
	v_cvt_pk_f16_f32 v190, v24, v25
	v_cvt_pk_f16_f32 v191, v26, v27
	global_store_dwordx4 v226, v[188:191], s[22:23] sc1
	s_waitcnt vmcnt(11)
	v_fma_mix_f32 v20, v200, v20, v196 op_sel_hi:[1,0,1]
	v_fma_mix_f32 v21, v200, v21, v196 op_sel:[1,0,1] op_sel_hi:[1,0,1]
	v_fma_mix_f32 v22, v201, v22, v197 op_sel_hi:[1,0,1]
	v_fma_mix_f32 v23, v201, v23, v197 op_sel:[1,0,1] op_sel_hi:[1,0,1]
	v_fma_mix_f32 v16, v202, v16, v198 op_sel_hi:[1,0,1]
	v_fma_mix_f32 v17, v202, v17, v198 op_sel:[1,0,1] op_sel_hi:[1,0,1]
	v_fma_mix_f32 v18, v203, v18, v199 op_sel_hi:[1,0,1]
	v_fma_mix_f32 v19, v203, v19, v199 op_sel:[1,0,1] op_sel_hi:[1,0,1]
	v_cvt_pk_f16_f32 v196, v20, v21
	v_cvt_pk_f16_f32 v197, v22, v23
	v_cvt_pk_f16_f32 v198, v16, v17
	v_cvt_pk_f16_f32 v199, v18, v19
	global_store_dwordx4 v226, v[196:199], s[22:23] offset:256 sc1
	s_waitcnt vmcnt(9)
	v_fma_mix_f32 v12, v208, v12, v204 op_sel_hi:[1,0,1]
	v_fma_mix_f32 v13, v208, v13, v204 op_sel:[1,0,1] op_sel_hi:[1,0,1]
	v_fma_mix_f32 v14, v209, v14, v205 op_sel_hi:[1,0,1]
	v_fma_mix_f32 v15, v209, v15, v205 op_sel:[1,0,1] op_sel_hi:[1,0,1]
	v_fma_mix_f32 v8, v210, v8, v206 op_sel_hi:[1,0,1]
	v_fma_mix_f32 v9, v210, v9, v206 op_sel:[1,0,1] op_sel_hi:[1,0,1]
	v_fma_mix_f32 v10, v211, v10, v207 op_sel_hi:[1,0,1]
	v_fma_mix_f32 v11, v211, v11, v207 op_sel:[1,0,1] op_sel_hi:[1,0,1]
	v_cvt_pk_f16_f32 v204, v12, v13
	v_cvt_pk_f16_f32 v205, v14, v15
	v_cvt_pk_f16_f32 v206, v8, v9
	v_cvt_pk_f16_f32 v207, v10, v11
	global_store_dwordx4 v227, v[204:207], s[22:23] sc1
	s_waitcnt vmcnt(7)
	v_fma_mix_f32 v4, v216, v4, v212 op_sel_hi:[1,0,1]
	v_fma_mix_f32 v5, v216, v5, v212 op_sel:[1,0,1] op_sel_hi:[1,0,1]
	v_fma_mix_f32 v6, v217, v6, v213 op_sel_hi:[1,0,1]
	v_fma_mix_f32 v7, v217, v7, v213 op_sel:[1,0,1] op_sel_hi:[1,0,1]
	v_fma_mix_f32 v0, v218, v0, v214 op_sel_hi:[1,0,1]
	v_fma_mix_f32 v1, v218, v1, v214 op_sel:[1,0,1] op_sel_hi:[1,0,1]
	v_fma_mix_f32 v2, v219, v2, v215 op_sel_hi:[1,0,1]
	v_fma_mix_f32 v3, v219, v3, v215 op_sel:[1,0,1] op_sel_hi:[1,0,1]
	v_cvt_pk_f16_f32 v212, v4, v5
	v_cvt_pk_f16_f32 v213, v6, v7
	v_cvt_pk_f16_f32 v214, v0, v1
	v_cvt_pk_f16_f32 v215, v2, v3
	global_store_dwordx4 v227, v[212:215], s[22:23] offset:256 sc1
	s_waitcnt vmcnt(0)
	s_barrier
	v_mbcnt_lo_u32_b32 v0, -1, 0
	v_mbcnt_hi_u32_b32 v0, -1, v0
	s_nop 0
	v_or_b32_e32 v0, s97, v0
	v_cmp_eq_u32_e32 vcc, 0, v0
	s_and_saveexec_b64 s[10:11], vcc
	s_cbranch_execz .LBB0_1199
	s_mov_b64 s[14:15], exec
	v_mbcnt_lo_u32_b32 v0, s14, 0
	v_mbcnt_hi_u32_b32 v0, s15, v0
	v_cmp_eq_u32_e32 vcc, 0, v0
	s_and_saveexec_b64 s[12:13], vcc
	s_cbranch_execz .LBB0_1238
	s_lshl_b32 s4, s4, 6
	s_lshl_b64 s[16:17], s[4:5], 2
	s_add_u32 s16, s56, s16
	s_addc_u32 s17, s57, s17
	s_bcnt1_i32_b64 s4, s[14:15]
	v_mov_b32_e32 v0, s4
	global_atomic_add v129, v0, s[16:17]
